# attention step loop: the 24 never-consumed clamped-tile prefetch loads of the last iteration run with one active lane (still counted in vmcnt) instead of fetching 24 KiB per wave and block
# baseline (speedup 1.0000x reference)
; #define AB_ISSUE(T, kf, vf) do { AB_GEOM(T); (void)tp; \
;         _Pragma("unroll") for (int i_ = 0; i_ < 4; ++i_) { int r_ = T0 + qoff + ((ub + lrow + 8 * i_) << ld); r_ = min(max(r_, 0), SEQ - 1); \
;             kf[i_] = *(const u32x4*)(kbase + (size_t)r_ * ZLD); vf[i_] = *(const u32x4*)(vbase + (size_t)r_ * ZLD); } } while (0)
; DI void attn_block(const Params& p, LAS unsigned char* lds, int bh, int blk, int wid, int lane) {
;     ...
;     for (int T = 0; T < 21; T += 3) {
;         AB_STEP(T, kfA, vfA); AB_ISSUE(T + 3, kfA, vfA);
;         AB_STEP(T + 1, kfB, vfB); AB_ISSUE(T + 4, kfB, vfB);
;         AB_STEP(T + 2, kfC, vfC); AB_ISSUE(T + 5, kfC, vfC);
;     }
.LBB0_389:
	s_mov_b64 s[96:97], exec
	s_cmp_lt_u32 s89, 18
	s_cselect_b64 exec, exec, 1
	v_mul_u32_u24_e32 v0, 0x2080, v145
	v_lshlrev_b64 v[2:3], 1, v[0:1]
	v_mul_u32_u24_e32 v0, 0x2080, v144
	v_lshl_add_u64 v[4:5], v[206:207], 0, v[2:3]
	v_lshlrev_b64 v[6:7], 1, v[0:1]
	v_mul_u32_u24_e32 v0, 0x2080, v153
	v_lshl_add_u64 v[8:9], v[206:207], 0, v[6:7]
	global_load_dwordx4 v[144:147], v[4:5], off
	global_load_dwordx4 v[148:151], v[8:9], off
	v_lshlrev_b64 v[4:5], 1, v[0:1]
	v_mul_u32_u24_e32 v0, 0x2080, v152
	v_lshl_add_u64 v[8:9], v[206:207], 0, v[4:5]
	v_lshlrev_b64 v[10:11], 1, v[0:1]
	v_lshl_add_u64 v[12:13], v[206:207], 0, v[10:11]
	global_load_dwordx4 v[152:155], v[8:9], off
	global_load_dwordx4 v[156:159], v[12:13], off
	v_lshl_add_u64 v[8:9], v[204:205], 0, v[10:11]
	v_lshl_add_u64 v[4:5], v[204:205], 0, v[4:5]
	global_load_dwordx4 v[164:167], v[8:9], off
	global_load_dwordx4 v[160:163], v[4:5], off
	v_lshl_add_u64 v[4:5], v[204:205], 0, v[6:7]
	v_lshl_add_u64 v[2:3], v[204:205], 0, v[2:3]
	global_load_dwordx4 v[172:175], v[4:5], off
	global_load_dwordx4 v[168:171], v[2:3], off
	s_mov_b64 exec, s[96:97]
	s_cmp_gt_u32 s89, 4
	s_cselect_b64 s[66:67], -1, 0
	s_cmp_gt_u32 s89, 9
	s_cselect_b64 s[60:61], -1, 0
	s_cmp_lt_u32 s89, 10
	s_cselect_b64 s[10:11], -1, 0
	s_and_b64 s[8:9], s[10:11], exec
	s_cselect_b32 s0, 1, 2
	s_cmp_lt_u32 s89, 5
	s_cselect_b64 s[8:9], -1, 0
	s_and_b64 s[72:73], s[8:9], exec
	s_mul_i32 s72, s89, 0xcd
	s_cselect_b32 s0, 0, s0
	s_bfe_u32 s72, s72, 0x6000a
	s_mul_i32 s72, s72, 5
	s_sub_i32 s92, s89, s72
	s_and_b32 s78, s92, 0xff
	s_lshl_b32 s79, s0, 1
	s_cmp_gt_u32 s89, 14
	s_cselect_b64 s[72:73], -1, 0
	v_cndmask_b32_e64 v2, 0, 1, s[72:73]
	v_cndmask_b32_e64 v0, v239, v232, s[8:9]
	v_or_b32_e32 v2, v238, v2
	v_cndmask_b32_e64 v201, v2, v0, s[10:11]
	v_lshl_add_u32 v220, v230, s79, v201
	s_cmp_lg_u32 s78, 0
	v_lshl_add_u32 v250, v240, s79, v201
	s_cbranch_scc0 .LBB0_391
	s_cmp_lg_u32 s78, 2
	s_cbranch_scc0 .LBB0_408
	s_branch .LBB0_415

; #define AB_ISSUE(T, kf, vf) do { AB_GEOM(T); (void)tp; \
;         _Pragma("unroll") for (int i_ = 0; i_ < 4; ++i_) { int r_ = T0 + qoff + ((ub + lrow + 8 * i_) << ld); r_ = min(max(r_, 0), SEQ - 1); \
;             kf[i_] = *(const u32x4*)(kbase + (size_t)r_ * ZLD); vf[i_] = *(const u32x4*)(vbase + (size_t)r_ * ZLD); } } while (0)
; DI void attn_block(const Params& p, LAS unsigned char* lds, int bh, int blk, int wid, int lane) {
;     ...
;         AB_STEP(T, kfA, vfA); AB_ISSUE(T + 3, kfA, vfA);
;         AB_STEP(T + 1, kfB, vfB); AB_ISSUE(T + 4, kfB, vfB);
;         AB_STEP(T + 2, kfC, vfC); AB_ISSUE(T + 5, kfC, vfC);
;     }
.LBB0_439:
	s_add_i32 s92, s89, 3
	s_min_i32 s10, s92, 19
	s_mul_hi_u32 s11, s10, 0xcccccccd
	s_lshr_b32 s11, s11, 2
	s_mul_i32 s11, s11, 5
	s_sub_i32 s10, s10, s11
	s_lshl_b32 s10, s10, 5
	s_lshl_b32 s0, s0, 1
	s_mov_b64 s[96:97], exec
	s_cmp_lt_u32 s89, 18
	s_cselect_b64 exec, exec, 1
	v_add_u32_e32 v6, s12, v0
	v_subrev_u32_e32 v7, s10, v231
	v_lshl_add_u32 v0, v7, s0, v6
	v_med3_i32 v0, v0, 0, v233
	v_mul_u32_u24_e32 v0, 0x2080, v0
	s_waitcnt lgkmcnt(4)
	v_lshlrev_b64 v[2:3], 1, v[0:1]
	v_or_b32_e32 v0, 8, v7
	v_lshl_add_u32 v0, v0, s0, v6
	v_med3_i32 v0, v0, 0, v233
	v_lshl_add_u64 v[4:5], v[206:207], 0, v[2:3]
	v_lshl_add_u64 v[2:3], v[204:205], 0, v[2:3]
	v_mul_u32_u24_e32 v0, 0x2080, v0
	global_load_dwordx4 v[80:83], v[4:5], off
	global_load_dwordx4 v[84:87], v[2:3], off
	v_lshlrev_b64 v[2:3], 1, v[0:1]
	v_or_b32_e32 v0, 16, v7
	v_lshl_add_u32 v0, v0, s0, v6
	v_med3_i32 v0, v0, 0, v233
	v_lshl_add_u64 v[4:5], v[206:207], 0, v[2:3]
	v_lshl_add_u64 v[2:3], v[204:205], 0, v[2:3]
	v_mul_u32_u24_e32 v0, 0x2080, v0
	global_load_dwordx4 v[88:91], v[4:5], off
	global_load_dwordx4 v[92:95], v[2:3], off
	v_lshlrev_b64 v[2:3], 1, v[0:1]
	v_or_b32_e32 v0, 24, v7
	v_lshl_add_u32 v0, v0, s0, v6
	v_med3_i32 v0, v0, 0, v233
	v_lshl_add_u64 v[4:5], v[206:207], 0, v[2:3]
	v_lshl_add_u64 v[2:3], v[204:205], 0, v[2:3]
	v_mul_u32_u24_e32 v0, 0x2080, v0
	global_load_dwordx4 v[96:99], v[4:5], off
	global_load_dwordx4 v[100:103], v[2:3], off
	v_lshlrev_b64 v[2:3], 1, v[0:1]
	v_lshl_add_u64 v[4:5], v[206:207], 0, v[2:3]
	v_lshl_add_u64 v[2:3], v[204:205], 0, v[2:3]
	global_load_dwordx4 v[112:115], v[4:5], off
	global_load_dwordx4 v[116:119], v[2:3], off
	s_mov_b64 exec, s[96:97]
	s_cmp_gt_u32 s89, 3
	s_cselect_b64 s[66:67], -1, 0
	s_cmp_gt_u32 s89, 8
	s_cselect_b64 s[60:61], -1, 0
	s_cmp_lt_u32 s89, 9
	s_cselect_b64 s[10:11], -1, 0
	s_and_b64 s[72:73], s[10:11], exec
	s_cselect_b32 s0, 1, 2
	s_cmp_lt_u32 s89, 4
	s_cselect_b64 vcc, -1, 0
	s_and_b64 s[72:73], vcc, exec
	s_cselect_b32 s0, 0, s0
	s_add_i32 s72, s89, 1
	s_and_b32 s73, s72, 0xff
	s_mulk_i32 s73, 0xcd
	s_bfe_u32 s73, s73, 0x6000a
	s_mul_i32 s73, s73, 5
	s_sub_i32 s93, s72, s73
	s_and_b32 s78, s93, 0xff
	s_cmp_gt_u32 s89, 13
	s_cselect_b64 s[72:73], -1, 0
	s_cmp_eq_u32 s78, 0
	s_cbranch_scc1 .LBB0_443
	s_mov_b64 s[74:75], 0
	s_branch .LBB0_444

; #define AB_ISSUE(T, kf, vf) do { AB_GEOM(T); (void)tp; \
;         _Pragma("unroll") for (int i_ = 0; i_ < 4; ++i_) { int r_ = T0 + qoff + ((ub + lrow + 8 * i_) << ld); r_ = min(max(r_, 0), SEQ - 1); \
;             kf[i_] = *(const u32x4*)(kbase + (size_t)r_ * ZLD); vf[i_] = *(const u32x4*)(vbase + (size_t)r_ * ZLD); } } while (0)
; DI void attn_block(const Params& p, LAS unsigned char* lds, int bh, int blk, int wid, int lane) {
;     ...
;     for (int T = 0; T < 21; T += 3) {
;         AB_STEP(T, kfA, vfA); AB_ISSUE(T + 3, kfA, vfA);
;         AB_STEP(T + 1, kfB, vfB); AB_ISSUE(T + 4, kfB, vfB);
;         AB_STEP(T + 2, kfC, vfC); AB_ISSUE(T + 5, kfC, vfC);
;     }
.LBB0_492:
	s_min_u32 s10, s89, 15
	s_add_i32 s10, s10, 4
	s_mul_i32 s11, s10, 52
	s_bfe_u32 s11, s11, 0x80008
	s_mul_i32 s11, s11, 5
	s_sub_i32 s10, s10, s11
	s_and_b32 s10, s10, 0xff
	s_lshl_b32 s10, s10, 5
	s_lshl_b32 s0, s0, 1
	s_mov_b64 s[96:97], exec
	s_cmp_lt_u32 s89, 18
	s_cselect_b64 exec, exec, 1
	v_add_u32_e32 v6, s12, v0
	v_subrev_u32_e32 v7, s10, v231
	v_lshl_add_u32 v0, v7, s0, v6
	v_med3_i32 v0, v0, 0, v233
	v_mul_u32_u24_e32 v0, 0x2080, v0
	s_waitcnt lgkmcnt(4)
	v_lshlrev_b64 v[2:3], 1, v[0:1]
	v_or_b32_e32 v0, 8, v7
	v_lshl_add_u32 v0, v0, s0, v6
	v_med3_i32 v0, v0, 0, v233
	v_lshl_add_u64 v[4:5], v[206:207], 0, v[2:3]
	v_lshl_add_u64 v[2:3], v[204:205], 0, v[2:3]
	v_mul_u32_u24_e32 v0, 0x2080, v0
	global_load_dwordx4 v[104:107], v[4:5], off
	global_load_dwordx4 v[108:111], v[2:3], off
	v_lshlrev_b64 v[2:3], 1, v[0:1]
	v_or_b32_e32 v0, 16, v7
	v_lshl_add_u32 v0, v0, s0, v6
	v_med3_i32 v0, v0, 0, v233
	v_lshl_add_u64 v[4:5], v[206:207], 0, v[2:3]
	v_lshl_add_u64 v[2:3], v[204:205], 0, v[2:3]
	v_mul_u32_u24_e32 v0, 0x2080, v0
	global_load_dwordx4 v[120:123], v[4:5], off
	global_load_dwordx4 v[124:127], v[2:3], off
	v_lshlrev_b64 v[2:3], 1, v[0:1]
	v_or_b32_e32 v0, 24, v7
	v_lshl_add_u32 v0, v0, s0, v6
	v_med3_i32 v0, v0, 0, v233
	v_lshl_add_u64 v[4:5], v[206:207], 0, v[2:3]
	v_lshl_add_u64 v[2:3], v[204:205], 0, v[2:3]
	v_mul_u32_u24_e32 v0, 0x2080, v0
	global_load_dwordx4 v[128:131], v[4:5], off
	global_load_dwordx4 v[132:135], v[2:3], off
	v_lshlrev_b64 v[2:3], 1, v[0:1]
	v_lshl_add_u64 v[4:5], v[206:207], 0, v[2:3]
	v_lshl_add_u64 v[2:3], v[204:205], 0, v[2:3]
	global_load_dwordx4 v[136:139], v[4:5], off
	global_load_dwordx4 v[140:143], v[2:3], off
	s_mov_b64 exec, s[96:97]
	s_cmp_gt_u32 s89, 17
	s_cselect_b64 s[60:61], -1, 0
	s_and_b64 vcc, exec, s[60:61]
	s_cbranch_vccnz .LBB0_388
	s_cmp_gt_u32 s89, 2
	s_cselect_b64 s[72:73], -1, 0
	s_cmp_gt_u32 s89, 7
	s_cselect_b64 s[66:67], -1, 0
	s_cmp_lt_u32 s89, 8
	s_cselect_b64 s[10:11], -1, 0
	s_and_b64 s[74:75], s[10:11], exec
	s_cselect_b32 s0, 1, 2
	s_cmp_lt_u32 s89, 3
	s_cselect_b64 vcc, -1, 0
	s_and_b64 s[74:75], vcc, exec
	s_cselect_b32 s0, 0, s0
	s_add_i32 s74, s89, 2
	s_and_b32 s75, s74, 0xff
	s_mulk_i32 s75, 0xcd
	s_bfe_u32 s75, s75, 0x6000a
	s_mul_i32 s75, s75, 5
	s_sub_i32 s95, s74, s75
	s_and_b32 s93, s95, 0xff
	s_cmp_gt_u32 s89, 12
	s_cselect_b64 s[78:79], -1, 0
	s_cmp_eq_u32 s93, 0
	s_cbranch_scc1 .LBB0_499
	s_mov_b64 s[74:75], 0
	s_branch .LBB0_500
